# diff and dilated pass-1 epilogues: gain loads hoisted with counted waits, row stores widened to dwordx4 via v_permlane32_swap
# speedup vs baseline: 1.0195x; 1.0047x over previous
.LBB0_658:
	s_andn2_b64 vcc, exec, s[64:65]
	s_waitcnt lgkmcnt(0)
	s_barrier
	s_cbranch_vccnz .LBB0_653
	v_cndmask_b32_e64 v84, v83, v84, s[8:9]
	v_add_u32_e32 v83, 0x400, v82
	ds_read2_b32 v[92:93], v82 offset1:32
	ds_read2_b32 v[94:95], v82 offset0:64 offset1:96
	ds_read2_b32 v[96:97], v83 offset1:32
	ds_read2_b32 v[98:99], v83 offset0:64 offset1:96
	v_add_u32_e32 v83, 0x800, v82
	ds_read2_b32 v[100:101], v83 offset1:32
	ds_read2_b32 v[102:103], v83 offset0:64 offset1:96
	v_add_u32_e32 v83, 0xc00, v82
	ds_read2_b32 v[104:105], v83 offset1:32
	ds_read2_b32 v[106:107], v83 offset0:64 offset1:96
	v_add_u32_e32 v83, 0x1000, v82
	ds_read2_b32 v[108:109], v83 offset1:32
	ds_read2_b32 v[110:111], v83 offset0:64 offset1:96
	v_add_u32_e32 v83, 0x1400, v82
	ds_read2_b32 v[112:113], v83 offset1:32
	ds_read2_b32 v[114:115], v83 offset0:64 offset1:96
	v_add_u32_e32 v83, 0x1800, v82
	ds_read2_b32 v[116:117], v83 offset1:32
	ds_read2_b32 v[118:119], v83 offset0:64 offset1:96
	v_add_u32_e32 v83, 0x1c00, v82
	ds_read2_b32 v[120:121], v83 offset1:32
	ds_read2_b32 v[122:123], v83 offset0:64 offset1:96
	v_add_u32_e32 v83, 0x2000, v82
	ds_read2_b32 v[124:125], v83 offset1:32
	ds_read2_b32 v[126:127], v83 offset0:64 offset1:96
	v_add_u32_e32 v83, 0x2400, v82
	ds_read2_b32 v[128:129], v83 offset1:32
	ds_read2_b32 v[130:131], v83 offset0:64 offset1:96
	v_add_u32_e32 v83, 0x2800, v82
	ds_read2_b32 v[132:133], v83 offset1:32
	ds_read2_b32 v[134:135], v83 offset0:64 offset1:96
	v_add_u32_e32 v83, 0x2c00, v82
	ds_read2_b32 v[136:137], v83 offset1:32
	ds_read2_b32 v[138:139], v83 offset0:64 offset1:96
	v_add_u32_e32 v83, 0x3000, v82
	ds_read2_b32 v[140:141], v83 offset1:32
	ds_read2_b32 v[142:143], v83 offset0:64 offset1:96
	v_add_u32_e32 v83, 0x3400, v82
	ds_read2_b32 v[144:145], v83 offset1:32
	ds_read2_b32 v[146:147], v83 offset0:64 offset1:96
	v_add_u32_e32 v83, 0x3800, v82
	v_add_u32_e32 v82, 0x3c00, v82
	ds_read2_b32 v[88:89], v83 offset0:64 offset1:96
	ds_read2_b32 v[90:91], v82 offset1:32
	ds_read2_b32 v[148:149], v83 offset1:32
	ds_read2_b32 v[150:151], v82 offset0:64 offset1:96
	v_lshlrev_b32_e32 v156, 2, v87
	v_ashrrev_i32_e32 v157, 31, v156
	s_waitcnt lgkmcnt(14)
	v_pk_fma_f32 v[92:93], v[50:51], v[84:85], v[92:93] op_sel_hi:[1,0,1] neg_lo:[0,0,1] neg_hi:[0,0,1]
	s_waitcnt lgkmcnt(3)
	v_pk_fma_f32 v[82:83], v[28:29], v[84:85], v[88:89] op_sel_hi:[1,0,1] neg_lo:[0,0,1] neg_hi:[0,0,1]
	s_waitcnt lgkmcnt(2)
	v_pk_fma_f32 v[28:29], v[30:31], v[84:85], v[90:91] op_sel_hi:[1,0,1] neg_lo:[0,0,1] neg_hi:[0,0,1]
	s_waitcnt lgkmcnt(0)
	v_pk_fma_f32 v[30:31], v[32:33], v[84:85], v[150:151] op_sel_hi:[1,0,1] neg_lo:[0,0,1] neg_hi:[0,0,1]
	v_lshl_add_u64 v[32:33], v[156:157], 2, s[10:11]
	global_load_dwordx4 v[88:91], v[32:33], off
	global_load_dwordx4 v[194:197], v[32:33], off offset:32
	global_load_dwordx4 v[198:201], v[32:33], off offset:64
	global_load_dwordx4 v[202:205], v[32:33], off offset:96
	global_load_dwordx4 v[206:209], v[32:33], off offset:128
	global_load_dwordx4 v[210:213], v[32:33], off offset:160
	global_load_dwordx4 v[214:217], v[32:33], off offset:192
	global_load_dwordx4 v[218:221], v[32:33], off offset:224
	global_load_dwordx4 v[226:229], v[32:33], off offset:256
	global_load_dwordx4 v[230:233], v[32:33], off offset:288
	global_load_dwordx4 v[234:237], v[32:33], off offset:320
	global_load_dwordx4 v[164:167], v[32:33], off offset:352
	global_load_dwordx4 v[168:171], v[32:33], off offset:384
	global_load_dwordx4 v[172:175], v[32:33], off offset:416
	v_pk_fma_f32 v[52:53], v[52:53], v[84:85], v[94:95] op_sel_hi:[1,0,1] neg_lo:[0,0,1] neg_hi:[0,0,1]
	v_pk_mul_f32 v[158:159], v[92:93], v[92:93]
	v_pk_mul_f32 v[94:95], v[52:53], v[52:53]
	v_pk_fma_f32 v[56:57], v[56:57], v[84:85], v[98:99] op_sel_hi:[1,0,1] neg_lo:[0,0,1] neg_hi:[0,0,1]
	v_pk_fma_f32 v[54:55], v[54:55], v[84:85], v[96:97] op_sel_hi:[1,0,1] neg_lo:[0,0,1] neg_hi:[0,0,1]
	v_pk_fma_f32 v[60:61], v[60:61], v[84:85], v[102:103] op_sel_hi:[1,0,1] neg_lo:[0,0,1] neg_hi:[0,0,1]
	v_pk_fma_f32 v[58:59], v[58:59], v[84:85], v[100:101] op_sel_hi:[1,0,1] neg_lo:[0,0,1] neg_hi:[0,0,1]
	v_pk_fma_f32 v[64:65], v[64:65], v[84:85], v[106:107] op_sel_hi:[1,0,1] neg_lo:[0,0,1] neg_hi:[0,0,1]
	v_pk_fma_f32 v[62:63], v[62:63], v[84:85], v[104:105] op_sel_hi:[1,0,1] neg_lo:[0,0,1] neg_hi:[0,0,1]
	v_pk_fma_f32 v[68:69], v[68:69], v[84:85], v[110:111] op_sel_hi:[1,0,1] neg_lo:[0,0,1] neg_hi:[0,0,1]
	v_pk_fma_f32 v[66:67], v[66:67], v[84:85], v[108:109] op_sel_hi:[1,0,1] neg_lo:[0,0,1] neg_hi:[0,0,1]
	v_pk_fma_f32 v[72:73], v[72:73], v[84:85], v[114:115] op_sel_hi:[1,0,1] neg_lo:[0,0,1] neg_hi:[0,0,1]
	v_pk_fma_f32 v[70:71], v[70:71], v[84:85], v[112:113] op_sel_hi:[1,0,1] neg_lo:[0,0,1] neg_hi:[0,0,1]
	v_pk_fma_f32 v[76:77], v[76:77], v[84:85], v[118:119] op_sel_hi:[1,0,1] neg_lo:[0,0,1] neg_hi:[0,0,1]
	v_pk_fma_f32 v[74:75], v[74:75], v[84:85], v[116:117] op_sel_hi:[1,0,1] neg_lo:[0,0,1] neg_hi:[0,0,1]
	v_pk_fma_f32 v[80:81], v[80:81], v[84:85], v[122:123] op_sel_hi:[1,0,1] neg_lo:[0,0,1] neg_hi:[0,0,1]
	v_pk_fma_f32 v[78:79], v[78:79], v[84:85], v[120:121] op_sel_hi:[1,0,1] neg_lo:[0,0,1] neg_hi:[0,0,1]
	v_pk_fma_f32 v[50:51], v[36:37], v[84:85], v[126:127] op_sel_hi:[1,0,1] neg_lo:[0,0,1] neg_hi:[0,0,1]
	v_pk_fma_f32 v[124:125], v[34:35], v[84:85], v[124:125] op_sel_hi:[1,0,1] neg_lo:[0,0,1] neg_hi:[0,0,1]
	v_pk_fma_f32 v[40:41], v[40:41], v[84:85], v[130:131] op_sel_hi:[1,0,1] neg_lo:[0,0,1] neg_hi:[0,0,1]
	v_pk_fma_f32 v[128:129], v[38:39], v[84:85], v[128:129] op_sel_hi:[1,0,1] neg_lo:[0,0,1] neg_hi:[0,0,1]
	v_pk_fma_f32 v[38:39], v[44:45], v[84:85], v[134:135] op_sel_hi:[1,0,1] neg_lo:[0,0,1] neg_hi:[0,0,1]
	v_pk_fma_f32 v[132:133], v[42:43], v[84:85], v[132:133] op_sel_hi:[1,0,1] neg_lo:[0,0,1] neg_hi:[0,0,1]
	v_pk_fma_f32 v[36:37], v[48:49], v[84:85], v[138:139] op_sel_hi:[1,0,1] neg_lo:[0,0,1] neg_hi:[0,0,1]
	v_pk_fma_f32 v[46:47], v[46:47], v[84:85], v[136:137] op_sel_hi:[1,0,1] neg_lo:[0,0,1] neg_hi:[0,0,1]
	v_pk_fma_f32 v[34:35], v[20:21], v[84:85], v[142:143] op_sel_hi:[1,0,1] neg_lo:[0,0,1] neg_hi:[0,0,1]
	v_pk_fma_f32 v[42:43], v[18:19], v[84:85], v[140:141] op_sel_hi:[1,0,1] neg_lo:[0,0,1] neg_hi:[0,0,1]
	v_pk_fma_f32 v[18:19], v[24:25], v[84:85], v[146:147] op_sel_hi:[1,0,1] neg_lo:[0,0,1] neg_hi:[0,0,1]
	v_pk_fma_f32 v[22:23], v[22:23], v[84:85], v[144:145] op_sel_hi:[1,0,1] neg_lo:[0,0,1] neg_hi:[0,0,1]
	v_pk_fma_f32 v[20:21], v[26:27], v[84:85], v[148:149] op_sel_hi:[1,0,1] neg_lo:[0,0,1] neg_hi:[0,0,1]
	v_add_f32_e32 v84, v158, v159
	v_add_f32_e32 v84, v84, v94
	v_pk_mul_f32 v[96:97], v[54:55], v[54:55]
	v_add_f32_e32 v84, v84, v95
	v_add_f32_e32 v84, v84, v96
	v_pk_mul_f32 v[98:99], v[56:57], v[56:57]
	v_add_f32_e32 v84, v84, v97
	v_add_f32_e32 v84, v84, v98
	v_pk_mul_f32 v[100:101], v[58:59], v[58:59]
	v_add_f32_e32 v84, v84, v99
	v_add_f32_e32 v84, v84, v100
	v_pk_mul_f32 v[102:103], v[60:61], v[60:61]
	v_add_f32_e32 v84, v84, v101
	v_add_f32_e32 v84, v84, v102
	v_pk_mul_f32 v[104:105], v[62:63], v[62:63]
	v_add_f32_e32 v84, v84, v103
	v_add_f32_e32 v84, v84, v104
	v_pk_mul_f32 v[106:107], v[64:65], v[64:65]
	v_add_f32_e32 v84, v84, v105
	v_add_f32_e32 v84, v84, v106
	v_pk_mul_f32 v[108:109], v[66:67], v[66:67]
	v_add_f32_e32 v84, v84, v107
	v_add_f32_e32 v84, v84, v108
	v_pk_mul_f32 v[110:111], v[68:69], v[68:69]
	v_add_f32_e32 v84, v84, v109
	v_add_f32_e32 v84, v84, v110
	v_pk_mul_f32 v[112:113], v[70:71], v[70:71]
	v_add_f32_e32 v84, v84, v111
	v_add_f32_e32 v84, v84, v112
	v_pk_mul_f32 v[114:115], v[72:73], v[72:73]
	v_add_f32_e32 v84, v84, v113
	v_add_f32_e32 v84, v84, v114
	v_pk_mul_f32 v[116:117], v[74:75], v[74:75]
	v_add_f32_e32 v84, v84, v115
	v_add_f32_e32 v84, v84, v116
	v_pk_mul_f32 v[118:119], v[76:77], v[76:77]
	v_add_f32_e32 v84, v84, v117
	v_add_f32_e32 v84, v84, v118
	v_pk_mul_f32 v[120:121], v[78:79], v[78:79]
	v_add_f32_e32 v84, v84, v119
	v_add_f32_e32 v84, v84, v120
	v_pk_mul_f32 v[122:123], v[80:81], v[80:81]
	v_add_f32_e32 v84, v84, v121
	v_add_f32_e32 v84, v84, v122
	v_pk_mul_f32 v[160:161], v[124:125], v[124:125]
	v_add_f32_e32 v84, v84, v123
	v_add_f32_e32 v84, v84, v160
	v_pk_mul_f32 v[126:127], v[50:51], v[50:51]
	v_add_f32_e32 v84, v84, v161
	v_add_f32_e32 v84, v84, v126
	v_pk_mul_f32 v[162:163], v[128:129], v[128:129]
	v_add_f32_e32 v84, v84, v127
	v_add_f32_e32 v84, v84, v162
	v_pk_mul_f32 v[130:131], v[40:41], v[40:41]
	v_add_f32_e32 v84, v84, v163
	v_add_f32_e32 v84, v84, v130
	v_pk_mul_f32 v[134:135], v[132:133], v[132:133]
	v_add_f32_e32 v84, v84, v131
	v_add_f32_e32 v84, v84, v134
	v_pk_mul_f32 v[44:45], v[38:39], v[38:39]
	v_add_f32_e32 v84, v84, v135
	v_add_f32_e32 v44, v84, v44
	v_pk_mul_f32 v[136:137], v[46:47], v[46:47]
	v_add_f32_e32 v44, v44, v45
	v_add_f32_e32 v44, v44, v136
	v_pk_mul_f32 v[48:49], v[36:37], v[36:37]
	v_add_f32_e32 v44, v44, v137
	v_add_f32_e32 v44, v44, v48
	v_pk_mul_f32 v[140:141], v[42:43], v[42:43]
	v_add_f32_e32 v44, v44, v49
	v_add_f32_e32 v44, v44, v140
	v_pk_mul_f32 v[138:139], v[34:35], v[34:35]
	v_add_f32_e32 v44, v44, v141
	v_add_f32_e32 v44, v44, v138
	v_pk_mul_f32 v[142:143], v[22:23], v[22:23]
	v_add_f32_e32 v44, v44, v139
	v_add_f32_e32 v44, v44, v142
	v_pk_mul_f32 v[24:25], v[18:19], v[18:19]
	v_add_f32_e32 v44, v44, v143
	v_add_f32_e32 v24, v44, v24
	v_pk_mul_f32 v[26:27], v[20:21], v[20:21]
	v_add_f32_e32 v24, v24, v25
	v_add_f32_e32 v24, v24, v26
	v_pk_mul_f32 v[152:153], v[82:83], v[82:83]
	v_add_f32_e32 v24, v24, v27
	v_add_f32_e32 v24, v24, v152
	v_pk_mul_f32 v[154:155], v[28:29], v[28:29]
	v_add_f32_e32 v24, v24, v153
	v_add_f32_e32 v24, v24, v154
	v_pk_mul_f32 v[150:151], v[30:31], v[30:31]
	v_add_f32_e32 v24, v24, v155
	v_add_f32_e32 v24, v24, v150
	v_add_f32_e32 v26, v24, v151
	ds_bpermute_b32 v27, v85, v26
	v_or_b32_e32 v24, s47, v86
	v_mov_b32_e32 v25, s70
	v_lshlrev_b64 v[24:25], 12, v[24:25]
	v_lshl_add_u64 v[24:25], s[14:15], 0, v[24:25]
	s_waitcnt lgkmcnt(0)
	v_add_f32_e32 v26, v26, v27
	v_mov_b32_e32 v27, 0x358637bd
	v_fmamk_f32 v26, v26, 0x3c000000, v27
	v_rsq_f32_e32 v26, v26
	s_lshl_b32 s12, s71, 1
	v_lshl_add_u64 v[24:25], v[24:25], 0, s[12:13]
	v_lshl_add_u64 v[44:45], v[156:157], 1, v[24:25]
	v_mbcnt_lo_u32_b32 v114, -1, 0
	v_mbcnt_hi_u32_b32 v114, -1, v114
	v_and_b32_e32 v114, 32, v114
	v_lshrrev_b32_e32 v114, 2, v114
	v_mov_b32_e32 v115, 0
	v_lshl_add_u64 v[112:113], v[44:45], 0, v[114:115]
	v_mul_f32_e32 v48, 0x3f4ccccd, v26
	v_pk_mul_f32 v[24:25], v[92:93], v[48:49] op_sel_hi:[1,0]
	v_pk_mul_f32 v[26:27], v[52:53], v[48:49] op_sel_hi:[1,0]
	global_load_dwordx4 v[94:97], v[32:33], off offset:448
	global_load_dwordx4 v[98:101], v[32:33], off offset:480
	s_waitcnt vmcnt(15)
	v_pk_mul_f32 v[24:25], v[88:89], v[24:25]
	v_pk_mul_f32 v[26:27], v[90:91], v[26:27]
	v_cvt_pk_bf16_f32 v104, v24, v25
	v_cvt_pk_bf16_f32 v105, v26, v27
	v_pk_mul_f32 v[52:53], v[54:55], v[48:49] op_sel_hi:[1,0]
	v_pk_mul_f32 v[54:55], v[60:61], v[48:49] op_sel_hi:[1,0]
	v_pk_mul_f32 v[50:51], v[50:51], v[48:49] op_sel_hi:[1,0]
	v_pk_mul_f32 v[40:41], v[40:41], v[48:49] op_sel_hi:[1,0]
	v_pk_mul_f32 v[38:39], v[38:39], v[48:49] op_sel_hi:[1,0]
	v_pk_mul_f32 v[36:37], v[36:37], v[48:49] op_sel_hi:[1,0]
	v_pk_mul_f32 v[34:35], v[34:35], v[48:49] op_sel_hi:[1,0]
	v_pk_mul_f32 v[22:23], v[22:23], v[48:49] op_sel_hi:[1,0]
	v_pk_mul_f32 v[18:19], v[18:19], v[48:49] op_sel_hi:[1,0]
	s_waitcnt vmcnt(14)
	v_pk_mul_f32 v[24:25], v[194:195], v[52:53]
	v_pk_mul_f32 v[52:53], v[56:57], v[48:49] op_sel_hi:[1,0]
	v_cvt_pk_bf16_f32 v106, v24, v25
	v_pk_mul_f32 v[26:27], v[196:197], v[52:53]
	v_pk_mul_f32 v[52:53], v[58:59], v[48:49] op_sel_hi:[1,0]
	v_cvt_pk_bf16_f32 v107, v26, v27
	s_nop 1
	v_permlane32_swap_b32 v104, v106
	v_permlane32_swap_b32 v105, v107
	global_store_dwordx4 v[112:113], v[104:107], off offset:2048
	s_nop 1
	s_waitcnt vmcnt(14)
	v_pk_mul_f32 v[24:25], v[198:199], v[52:53]
	v_pk_mul_f32 v[26:27], v[200:201], v[54:55]
	v_cvt_pk_bf16_f32 v104, v24, v25
	v_cvt_pk_bf16_f32 v105, v26, v27
	v_pk_mul_f32 v[52:53], v[62:63], v[48:49] op_sel_hi:[1,0]
	v_pk_mul_f32 v[54:55], v[64:65], v[48:49] op_sel_hi:[1,0]
	s_waitcnt vmcnt(13)
	v_pk_mul_f32 v[24:25], v[202:203], v[52:53]
	v_pk_mul_f32 v[26:27], v[204:205], v[54:55]
	v_cvt_pk_bf16_f32 v106, v24, v25
	v_cvt_pk_bf16_f32 v107, v26, v27
	s_nop 1
	v_permlane32_swap_b32 v104, v106
	v_permlane32_swap_b32 v105, v107
	global_store_dwordx4 v[112:113], v[104:107], off offset:2080
	s_nop 1
	v_pk_mul_f32 v[52:53], v[66:67], v[48:49] op_sel_hi:[1,0]
	v_pk_mul_f32 v[54:55], v[68:69], v[48:49] op_sel_hi:[1,0]
	s_waitcnt vmcnt(13)
	v_pk_mul_f32 v[24:25], v[52:53], v[206:207]
	v_pk_mul_f32 v[26:27], v[54:55], v[208:209]
	v_cvt_pk_bf16_f32 v104, v24, v25
	v_cvt_pk_bf16_f32 v105, v26, v27
	v_pk_mul_f32 v[52:53], v[70:71], v[48:49] op_sel_hi:[1,0]
	v_pk_mul_f32 v[54:55], v[72:73], v[48:49] op_sel_hi:[1,0]
	s_waitcnt vmcnt(12)
	v_pk_mul_f32 v[24:25], v[52:53], v[210:211]
	v_pk_mul_f32 v[26:27], v[54:55], v[212:213]
	v_cvt_pk_bf16_f32 v106, v24, v25
	v_cvt_pk_bf16_f32 v107, v26, v27
	s_nop 1
	v_permlane32_swap_b32 v104, v106
	v_permlane32_swap_b32 v105, v107
	global_store_dwordx4 v[112:113], v[104:107], off offset:2112
	s_nop 1
	v_pk_mul_f32 v[52:53], v[74:75], v[48:49] op_sel_hi:[1,0]
	v_pk_mul_f32 v[54:55], v[76:77], v[48:49] op_sel_hi:[1,0]
	s_waitcnt vmcnt(12)
	v_pk_mul_f32 v[24:25], v[52:53], v[214:215]
	v_pk_mul_f32 v[26:27], v[54:55], v[216:217]
	v_cvt_pk_bf16_f32 v104, v24, v25
	v_cvt_pk_bf16_f32 v105, v26, v27
	v_pk_mul_f32 v[52:53], v[78:79], v[48:49] op_sel_hi:[1,0]
	v_pk_mul_f32 v[54:55], v[80:81], v[48:49] op_sel_hi:[1,0]
	s_waitcnt vmcnt(11)
	v_pk_mul_f32 v[24:25], v[52:53], v[218:219]
	v_pk_mul_f32 v[26:27], v[54:55], v[220:221]
	v_cvt_pk_bf16_f32 v106, v24, v25
	v_cvt_pk_bf16_f32 v107, v26, v27
	s_nop 1
	v_permlane32_swap_b32 v104, v106
	v_permlane32_swap_b32 v105, v107
	global_store_dwordx4 v[112:113], v[104:107], off offset:2144
	s_nop 1
	v_pk_mul_f32 v[52:53], v[124:125], v[48:49] op_sel_hi:[1,0]
	s_waitcnt vmcnt(11)
	v_pk_mul_f32 v[26:27], v[50:51], v[228:229]
	v_pk_mul_f32 v[24:25], v[52:53], v[226:227]
	v_pk_mul_f32 v[50:51], v[128:129], v[48:49] op_sel_hi:[1,0]
	v_cvt_pk_bf16_f32 v104, v24, v25
	v_cvt_pk_bf16_f32 v105, v26, v27
	s_waitcnt vmcnt(10)
	v_pk_mul_f32 v[24:25], v[50:51], v[230:231]
	v_pk_mul_f32 v[26:27], v[40:41], v[232:233]
	v_cvt_pk_bf16_f32 v106, v24, v25
	v_cvt_pk_bf16_f32 v107, v26, v27
	s_nop 1
	v_permlane32_swap_b32 v104, v106
	v_permlane32_swap_b32 v105, v107
	global_store_dwordx4 v[112:113], v[104:107], off offset:2176
	s_nop 1
	v_pk_mul_f32 v[40:41], v[132:133], v[48:49] op_sel_hi:[1,0]
	s_waitcnt vmcnt(10)
	v_pk_mul_f32 v[26:27], v[38:39], v[236:237]
	v_pk_mul_f32 v[24:25], v[40:41], v[234:235]
	v_pk_mul_f32 v[38:39], v[46:47], v[48:49] op_sel_hi:[1,0]
	v_cvt_pk_bf16_f32 v104, v24, v25
	v_cvt_pk_bf16_f32 v105, v26, v27
	s_waitcnt vmcnt(9)
	v_pk_mul_f32 v[24:25], v[38:39], v[164:165]
	v_pk_mul_f32 v[26:27], v[36:37], v[166:167]
	v_cvt_pk_bf16_f32 v106, v24, v25
	v_cvt_pk_bf16_f32 v107, v26, v27
	s_nop 1
	v_permlane32_swap_b32 v104, v106
	v_permlane32_swap_b32 v105, v107
	global_store_dwordx4 v[112:113], v[104:107], off offset:2208
	s_nop 1
	v_pk_mul_f32 v[36:37], v[42:43], v[48:49] op_sel_hi:[1,0]
	s_waitcnt vmcnt(9)
	v_pk_mul_f32 v[26:27], v[34:35], v[170:171]
	v_pk_mul_f32 v[24:25], v[36:37], v[168:169]
	s_nop 0
	v_cvt_pk_bf16_f32 v104, v24, v25
	v_cvt_pk_bf16_f32 v105, v26, v27
	s_waitcnt vmcnt(8)
	v_pk_mul_f32 v[22:23], v[22:23], v[172:173]
	v_pk_mul_f32 v[18:19], v[18:19], v[174:175]
	v_cvt_pk_bf16_f32 v106, v22, v23
	v_cvt_pk_bf16_f32 v107, v18, v19
	s_nop 1
	v_permlane32_swap_b32 v104, v106
	v_permlane32_swap_b32 v105, v107
	global_store_dwordx4 v[112:113], v[104:107], off offset:2240
	s_nop 1
	v_pk_mul_f32 v[18:19], v[20:21], v[48:49] op_sel_hi:[1,0]
	v_pk_mul_f32 v[20:21], v[82:83], v[48:49] op_sel_hi:[1,0]
	s_waitcnt vmcnt(8)
	v_pk_mul_f32 v[18:19], v[18:19], v[94:95]
	v_pk_mul_f32 v[20:21], v[20:21], v[96:97]
	v_cvt_pk_bf16_f32 v104, v18, v19
	v_cvt_pk_bf16_f32 v105, v20, v21
	v_pk_mul_f32 v[22:23], v[28:29], v[48:49] op_sel_hi:[1,0]
	v_pk_mul_f32 v[24:25], v[30:31], v[48:49] op_sel_hi:[1,0]
	s_waitcnt vmcnt(7)
	v_pk_mul_f32 v[18:19], v[22:23], v[98:99]
	v_pk_mul_f32 v[20:21], v[24:25], v[100:101]
	v_cvt_pk_bf16_f32 v106, v18, v19
	v_cvt_pk_bf16_f32 v107, v20, v21
	s_nop 1
	v_permlane32_swap_b32 v104, v106
	v_permlane32_swap_b32 v105, v107
	global_store_dwordx4 v[112:113], v[104:107], off offset:2272
	s_nop 1
	s_branch .LBB0_653

.LBB0_662:
	v_mov_b32_e32 v80, 0
	v_mov_b32_e32 v81, s43
	v_mbcnt_lo_u32_b32 v80, -1, v80
	v_mbcnt_hi_u32_b32 v84, -1, v80
	v_lshlrev_b32_e32 v80, 4, v84
	v_and_b32_e32 v80, 0x1f0, v80
	v_or_b32_e32 v80, s56, v80
	v_or_b32_e32 v80, s42, v80
	v_lshlrev_b64 v[90:91], 12, v[80:81]
	v_lshlrev_b64 v[80:81], 5, v[80:81]
	v_lshl_add_u64 v[80:81], s[18:19], 0, v[80:81]
	s_lshl_b32 s20, s51, 2
	v_lshl_add_u64 v[80:81], v[80:81], 0, s[20:21]
	global_load_dword v154, v[80:81], off
	v_ashrrev_i32_e32 v80, 3, v84
	v_and_b32_e32 v92, -4, v80
	v_lshl_or_b32 v82, s51, 9, v90
	v_mov_b32_e32 v83, v91
	v_ashrrev_i32_e32 v93, 31, v92
	v_lshl_add_u64 v[82:83], s[16:17], 0, v[82:83]
	v_lshlrev_b64 v[80:81], 2, v[92:93]
	s_waitcnt vmcnt(7)
	v_lshl_add_u64 v[150:151], v[82:83], 0, v[80:81]
	v_lshlrev_b32_e32 v82, 2, v84
	global_load_dwordx4 v[94:97], v[150:151], off offset:448
	global_load_dwordx4 v[98:101], v[150:151], off offset:480
	global_load_dwordx4 v[102:105], v[150:151], off
	global_load_dwordx4 v[106:109], v[150:151], off offset:32
	global_load_dwordx4 v[110:113], v[150:151], off offset:64
	global_load_dwordx4 v[114:117], v[150:151], off offset:96
	global_load_dwordx4 v[118:121], v[150:151], off offset:128
	global_load_dwordx4 v[122:125], v[150:151], off offset:160
	global_load_dwordx4 v[126:129], v[150:151], off offset:192
	s_waitcnt vmcnt(14)
	v_xor_b32_e32 v158, 0x80, v82
	ds_bpermute_b32 v134, v158, v232
	v_lshl_add_u64 v[88:89], s[38:39], 0, v[80:81]
	global_load_dwordx4 v[130:133], v[150:151], off offset:224
	global_load_dwordx4 v[84:87], v[150:151], off offset:416
	global_load_dwordx4 v[80:83], v[88:89], off
	s_lshl_b32 s20, s50, 1
	s_waitcnt lgkmcnt(0)
	v_add_f32_e32 v155, v232, v134
	global_load_dwordx4 v[134:137], v[150:151], off offset:256
	global_load_dwordx4 v[138:141], v[150:151], off offset:288
	global_load_dwordx4 v[142:145], v[150:151], off offset:320
	global_load_dwordx4 v[146:149], v[150:151], off offset:352
	s_nop 0
	global_load_dwordx4 v[150:153], v[150:151], off offset:384
	s_add_i32 s60, s60, s62
	s_cmpk_gt_i32 s60, 0x7ff
	s_waitcnt vmcnt(17)
	v_add_f32_e32 v154, v154, v155
	v_div_scale_f32 v155, s[10:11], v154, v154, 1.0
	s_waitcnt vmcnt(16)
	v_pk_add_f32 v[24:25], v[24:25], v[94:95]
	s_waitcnt vmcnt(15)
	v_pk_add_f32 v[94:95], v[28:29], v[98:99]
	v_rcp_f32_e32 v28, v155
	v_div_scale_f32 v156, vcc, 1.0, v154, 1.0
	v_pk_add_f32 v[26:27], v[26:27], v[96:97]
	v_fma_f32 v29, -v155, v28, 1.0
	v_fmac_f32_e32 v28, v29, v28
	v_mul_f32_e32 v29, v156, v28
	v_pk_add_f32 v[96:97], v[30:31], v[100:101]
	v_fma_f32 v30, -v155, v29, v156
	v_fmac_f32_e32 v29, v30, v28
	v_fma_f32 v30, -v155, v29, v156
	v_div_fmas_f32 v28, v30, v28, v29
	s_waitcnt vmcnt(14)
	v_pk_add_f32 v[64:65], v[64:65], v[102:103]
	v_div_fixup_f32 v98, v28, v154, 1.0
	v_pk_add_f32 v[66:67], v[66:67], v[104:105]
	v_pk_mul_f32 v[64:65], v[98:99], v[64:65] op_sel_hi:[0,1]
	s_waitcnt vmcnt(13)
	v_pk_add_f32 v[68:69], v[68:69], v[106:107]
	v_pk_mul_f32 v[66:67], v[98:99], v[66:67] op_sel_hi:[0,1]
	v_pk_mul_f32 v[106:107], v[64:65], v[64:65]
	s_waitcnt vmcnt(0)
	global_load_dwordx4 v[160:163], v[88:89], off offset:32
	global_load_dwordx4 v[164:167], v[88:89], off offset:64
	global_load_dwordx4 v[168:171], v[88:89], off offset:96
	global_load_dwordx4 v[172:175], v[88:89], off offset:128
	global_load_dwordx4 v[176:179], v[88:89], off offset:160
	global_load_dwordx4 v[180:183], v[88:89], off offset:192
	global_load_dwordx4 v[184:187], v[88:89], off offset:224
	global_load_dwordx4 v[188:191], v[88:89], off offset:256
	global_load_dwordx4 v[192:195], v[88:89], off offset:288
	global_load_dwordx4 v[196:199], v[88:89], off offset:320
	global_load_dwordx4 v[200:203], v[88:89], off offset:352
	global_load_dwordx4 v[204:207], v[88:89], off offset:384
	global_load_dwordx4 v[234:237], v[88:89], off offset:416
	global_load_dwordx4 v[238:241], v[88:89], off offset:448
	global_load_dwordx4 v[242:245], v[88:89], off offset:480
	v_pk_add_f32 v[16:17], v[16:17], v[150:151]
	v_pk_mul_f32 v[104:105], v[66:67], v[66:67]
	v_pk_mul_f32 v[150:151], v[98:99], v[16:17] op_sel_hi:[0,1]
	v_pk_add_f32 v[16:17], v[22:23], v[86:87]
	v_add_f32_e32 v86, v106, v107
	v_pk_mul_f32 v[68:69], v[98:99], v[68:69] op_sel_hi:[0,1]
	v_add_f32_e32 v86, v104, v86
	v_pk_add_f32 v[70:71], v[70:71], v[108:109]
	v_pk_add_f32 v[72:73], v[72:73], v[110:111]
	v_pk_mul_f32 v[110:111], v[68:69], v[68:69]
	v_add_f32_e32 v86, v105, v86
	v_pk_mul_f32 v[70:71], v[98:99], v[70:71] op_sel_hi:[0,1]
	v_add_f32_e32 v86, v110, v86
	v_pk_mul_f32 v[108:109], v[70:71], v[70:71]
	v_add_f32_e32 v86, v111, v86
	v_pk_mul_f32 v[72:73], v[98:99], v[72:73] op_sel_hi:[0,1]
	v_add_f32_e32 v86, v108, v86
	v_pk_add_f32 v[74:75], v[74:75], v[112:113]
	v_pk_add_f32 v[76:77], v[76:77], v[114:115]
	v_pk_mul_f32 v[114:115], v[72:73], v[72:73]
	v_add_f32_e32 v86, v109, v86
	v_pk_mul_f32 v[74:75], v[98:99], v[74:75] op_sel_hi:[0,1]
	v_add_f32_e32 v86, v114, v86
	v_pk_mul_f32 v[112:113], v[74:75], v[74:75]
	v_add_f32_e32 v86, v115, v86
	v_pk_mul_f32 v[76:77], v[98:99], v[76:77] op_sel_hi:[0,1]
	v_add_f32_e32 v86, v112, v86
	v_pk_add_f32 v[78:79], v[78:79], v[116:117]
	v_pk_add_f32 v[48:49], v[48:49], v[118:119]
	v_pk_mul_f32 v[118:119], v[76:77], v[76:77]
	v_add_f32_e32 v86, v113, v86
	v_pk_mul_f32 v[78:79], v[98:99], v[78:79] op_sel_hi:[0,1]
	v_add_f32_e32 v86, v118, v86
	v_pk_mul_f32 v[116:117], v[78:79], v[78:79]
	v_add_f32_e32 v86, v119, v86
	v_pk_mul_f32 v[48:49], v[98:99], v[48:49] op_sel_hi:[0,1]
	v_add_f32_e32 v86, v116, v86
	v_pk_add_f32 v[50:51], v[50:51], v[120:121]
	v_pk_add_f32 v[52:53], v[52:53], v[122:123]
	v_pk_mul_f32 v[122:123], v[48:49], v[48:49]
	v_add_f32_e32 v86, v117, v86
	v_pk_mul_f32 v[50:51], v[98:99], v[50:51] op_sel_hi:[0,1]
	v_add_f32_e32 v86, v122, v86
	v_pk_mul_f32 v[120:121], v[50:51], v[50:51]
	v_add_f32_e32 v86, v123, v86
	v_pk_mul_f32 v[52:53], v[98:99], v[52:53] op_sel_hi:[0,1]
	v_add_f32_e32 v86, v120, v86
	v_pk_add_f32 v[54:55], v[54:55], v[124:125]
	v_pk_mul_f32 v[154:155], v[52:53], v[52:53]
	v_add_f32_e32 v86, v121, v86
	v_pk_mul_f32 v[54:55], v[98:99], v[54:55] op_sel_hi:[0,1]
	v_add_f32_e32 v86, v154, v86
	v_pk_mul_f32 v[124:125], v[54:55], v[54:55]
	v_pk_add_f32 v[56:57], v[56:57], v[126:127]
	v_add_f32_e32 v86, v155, v86
	v_pk_mul_f32 v[56:57], v[98:99], v[56:57] op_sel_hi:[0,1]
	v_add_f32_e32 v86, v124, v86
	v_pk_add_f32 v[58:59], v[58:59], v[128:129]
	v_pk_mul_f32 v[126:127], v[56:57], v[56:57]
	v_add_f32_e32 v86, v125, v86
	v_pk_mul_f32 v[58:59], v[98:99], v[58:59] op_sel_hi:[0,1]
	v_add_f32_e32 v86, v126, v86
	v_pk_mul_f32 v[128:129], v[58:59], v[58:59]
	v_pk_add_f32 v[60:61], v[60:61], v[130:131]
	v_add_f32_e32 v86, v127, v86
	v_pk_mul_f32 v[60:61], v[98:99], v[60:61] op_sel_hi:[0,1]
	v_add_f32_e32 v86, v128, v86
	v_pk_add_f32 v[62:63], v[62:63], v[132:133]
	v_pk_mul_f32 v[130:131], v[60:61], v[60:61]
	v_add_f32_e32 v86, v129, v86
	v_pk_mul_f32 v[62:63], v[98:99], v[62:63] op_sel_hi:[0,1]
	v_add_f32_e32 v86, v130, v86
	v_pk_mul_f32 v[132:133], v[62:63], v[62:63]
	v_pk_add_f32 v[32:33], v[32:33], v[134:135]
	v_add_f32_e32 v86, v131, v86
	v_pk_mul_f32 v[32:33], v[98:99], v[32:33] op_sel_hi:[0,1]
	v_add_f32_e32 v86, v132, v86
	v_pk_add_f32 v[34:35], v[34:35], v[136:137]
	v_pk_mul_f32 v[134:135], v[32:33], v[32:33]
	v_add_f32_e32 v86, v133, v86
	v_pk_mul_f32 v[34:35], v[98:99], v[34:35] op_sel_hi:[0,1]
	v_add_f32_e32 v86, v134, v86
	v_pk_mul_f32 v[136:137], v[34:35], v[34:35]
	v_pk_add_f32 v[36:37], v[36:37], v[138:139]
	v_add_f32_e32 v86, v135, v86
	v_pk_mul_f32 v[36:37], v[98:99], v[36:37] op_sel_hi:[0,1]
	v_add_f32_e32 v86, v136, v86
	v_pk_add_f32 v[38:39], v[38:39], v[140:141]
	v_pk_mul_f32 v[138:139], v[36:37], v[36:37]
	v_add_f32_e32 v86, v137, v86
	v_pk_mul_f32 v[38:39], v[98:99], v[38:39] op_sel_hi:[0,1]
	v_add_f32_e32 v86, v138, v86
	v_pk_mul_f32 v[140:141], v[38:39], v[38:39]
	v_pk_add_f32 v[40:41], v[40:41], v[142:143]
	v_add_f32_e32 v86, v139, v86
	v_pk_mul_f32 v[40:41], v[98:99], v[40:41] op_sel_hi:[0,1]
	v_add_f32_e32 v86, v140, v86
	v_pk_add_f32 v[42:43], v[42:43], v[144:145]
	v_pk_mul_f32 v[142:143], v[40:41], v[40:41]
	v_add_f32_e32 v86, v141, v86
	v_pk_mul_f32 v[42:43], v[98:99], v[42:43] op_sel_hi:[0,1]
	v_add_f32_e32 v86, v142, v86
	v_pk_mul_f32 v[144:145], v[42:43], v[42:43]
	v_pk_add_f32 v[44:45], v[44:45], v[146:147]
	v_add_f32_e32 v86, v143, v86
	v_pk_mul_f32 v[44:45], v[98:99], v[44:45] op_sel_hi:[0,1]
	v_add_f32_e32 v86, v144, v86
	v_pk_add_f32 v[46:47], v[46:47], v[148:149]
	v_pk_mul_f32 v[146:147], v[44:45], v[44:45]
	v_add_f32_e32 v86, v145, v86
	v_pk_mul_f32 v[46:47], v[98:99], v[46:47] op_sel_hi:[0,1]
	v_add_f32_e32 v86, v146, v86
	v_pk_mul_f32 v[148:149], v[46:47], v[46:47]
	v_add_f32_e32 v86, v147, v86
	v_add_f32_e32 v86, v148, v86
	v_pk_add_f32 v[18:19], v[18:19], v[152:153]
	v_pk_mul_f32 v[156:157], v[150:151], v[150:151]
	v_add_f32_e32 v86, v149, v86
	v_pk_mul_f32 v[18:19], v[98:99], v[18:19] op_sel_hi:[0,1]
	v_add_f32_e32 v86, v156, v86
	v_pk_mul_f32 v[152:153], v[18:19], v[18:19]
	v_pk_add_f32 v[20:21], v[20:21], v[84:85]
	v_add_f32_e32 v86, v157, v86
	v_pk_mul_f32 v[84:85], v[98:99], v[20:21] op_sel_hi:[0,1]
	v_add_f32_e32 v86, v152, v86
	v_pk_mul_f32 v[20:21], v[84:85], v[84:85]
	v_add_f32_e32 v86, v153, v86
	v_pk_mul_f32 v[16:17], v[98:99], v[16:17] op_sel_hi:[0,1]
	v_add_f32_e32 v20, v20, v86
	v_pk_mul_f32 v[22:23], v[16:17], v[16:17]
	v_add_f32_e32 v20, v21, v20
	v_pk_mul_f32 v[30:31], v[98:99], v[24:25] op_sel_hi:[0,1]
	v_add_f32_e32 v20, v22, v20
	v_pk_mul_f32 v[24:25], v[98:99], v[94:95] op_sel_hi:[0,1]
	v_pk_mul_f32 v[94:95], v[30:31], v[30:31]
	v_add_f32_e32 v20, v23, v20
	v_pk_mul_f32 v[28:29], v[98:99], v[26:27] op_sel_hi:[0,1]
	v_add_f32_e32 v20, v94, v20
	v_pk_mul_f32 v[26:27], v[98:99], v[96:97] op_sel_hi:[0,1]
	v_pk_mul_f32 v[96:97], v[28:29], v[28:29]
	v_add_f32_e32 v20, v95, v20
	v_add_f32_e32 v20, v96, v20
	v_pk_mul_f32 v[100:101], v[24:25], v[24:25]
	v_add_f32_e32 v20, v97, v20
	v_add_f32_e32 v20, v100, v20
	v_pk_mul_f32 v[102:103], v[26:27], v[26:27]
	v_add_f32_e32 v20, v101, v20
	v_add_f32_e32 v20, v102, v20
	v_add_f32_e32 v22, v103, v20
	ds_bpermute_b32 v23, v158, v22
	v_lshl_add_u64 v[20:21], s[14:15], 0, v[90:91]
	v_lshl_add_u64 v[20:21], v[20:21], 0, s[20:21]
	v_lshl_add_u64 v[90:91], v[92:93], 1, v[20:21]
	v_mbcnt_lo_u32_b32 v246, -1, 0
	v_mbcnt_hi_u32_b32 v246, -1, v246
	v_and_b32_e32 v246, 32, v246
	v_lshrrev_b32_e32 v246, 2, v246
	v_mov_b32_e32 v247, 0
	v_lshl_add_u64 v[252:253], v[90:91], 0, v[246:247]
	s_waitcnt lgkmcnt(0)
	v_add_f32_e32 v22, v22, v23
	v_fmamk_f32 v22, v22, 0x3c000000, v230
	v_rsq_f32_e32 v86, v22
	s_nop 0
	v_pk_mul_f32 v[20:21], v[64:65], v[86:87] op_sel_hi:[1,0]
	v_pk_mul_f32 v[22:23], v[66:67], v[86:87] op_sel_hi:[1,0]
	v_pk_mul_f32 v[20:21], v[80:81], v[20:21]
	v_pk_mul_f32 v[22:23], v[82:83], v[22:23]
	v_cvt_pk_bf16_f32 v248, v20, v21
	v_cvt_pk_bf16_f32 v249, v22, v23
	v_pk_mul_f32 v[64:65], v[68:69], v[86:87] op_sel_hi:[1,0]
	v_pk_mul_f32 v[66:67], v[70:71], v[86:87] op_sel_hi:[1,0]
	v_pk_mul_f32 v[48:49], v[48:49], v[86:87] op_sel_hi:[1,0]
	v_pk_mul_f32 v[50:51], v[50:51], v[86:87] op_sel_hi:[1,0]
	v_pk_mul_f32 v[32:33], v[32:33], v[86:87] op_sel_hi:[1,0]
	v_pk_mul_f32 v[34:35], v[34:35], v[86:87] op_sel_hi:[1,0]
	v_pk_mul_f32 v[18:19], v[18:19], v[86:87] op_sel_hi:[1,0]
	v_pk_mul_f32 v[16:17], v[16:17], v[86:87] op_sel_hi:[1,0]
	s_waitcnt vmcnt(14)
	v_pk_mul_f32 v[20:21], v[160:161], v[64:65]
	v_pk_mul_f32 v[22:23], v[162:163], v[66:67]
	v_cvt_pk_bf16_f32 v250, v20, v21
	v_cvt_pk_bf16_f32 v251, v22, v23
	s_nop 1
	v_permlane32_swap_b32 v248, v250
	v_permlane32_swap_b32 v249, v251
	global_store_dwordx4 v[252:253], v[248:251], off offset:0
	s_nop 1
	v_pk_mul_f32 v[64:65], v[72:73], v[86:87] op_sel_hi:[1,0]
	v_pk_mul_f32 v[66:67], v[74:75], v[86:87] op_sel_hi:[1,0]
	s_waitcnt vmcnt(14)
	v_pk_mul_f32 v[20:21], v[164:165], v[64:65]
	v_pk_mul_f32 v[22:23], v[166:167], v[66:67]
	v_cvt_pk_bf16_f32 v248, v20, v21
	v_cvt_pk_bf16_f32 v249, v22, v23
	v_pk_mul_f32 v[64:65], v[76:77], v[86:87] op_sel_hi:[1,0]
	v_pk_mul_f32 v[66:67], v[78:79], v[86:87] op_sel_hi:[1,0]
	s_waitcnt vmcnt(13)
	v_pk_mul_f32 v[20:21], v[168:169], v[64:65]
	v_pk_mul_f32 v[22:23], v[170:171], v[66:67]
	v_cvt_pk_bf16_f32 v250, v20, v21
	v_cvt_pk_bf16_f32 v251, v22, v23
	s_nop 1
	v_permlane32_swap_b32 v248, v250
	v_permlane32_swap_b32 v249, v251
	global_store_dwordx4 v[252:253], v[248:251], off offset:32
	s_nop 1
	s_waitcnt vmcnt(13)
	v_pk_mul_f32 v[20:21], v[172:173], v[48:49]
	v_pk_mul_f32 v[22:23], v[174:175], v[50:51]
	v_cvt_pk_bf16_f32 v248, v20, v21
	v_cvt_pk_bf16_f32 v249, v22, v23
	v_pk_mul_f32 v[48:49], v[52:53], v[86:87] op_sel_hi:[1,0]
	v_pk_mul_f32 v[50:51], v[54:55], v[86:87] op_sel_hi:[1,0]
	s_waitcnt vmcnt(12)
	v_pk_mul_f32 v[20:21], v[176:177], v[48:49]
	v_pk_mul_f32 v[22:23], v[178:179], v[50:51]
	v_cvt_pk_bf16_f32 v250, v20, v21
	v_cvt_pk_bf16_f32 v251, v22, v23
	s_nop 1
	v_permlane32_swap_b32 v248, v250
	v_permlane32_swap_b32 v249, v251
	global_store_dwordx4 v[252:253], v[248:251], off offset:64
	s_nop 1
	v_pk_mul_f32 v[48:49], v[56:57], v[86:87] op_sel_hi:[1,0]
	v_pk_mul_f32 v[50:51], v[58:59], v[86:87] op_sel_hi:[1,0]
	s_waitcnt vmcnt(12)
	v_pk_mul_f32 v[20:21], v[180:181], v[48:49]
	v_pk_mul_f32 v[22:23], v[182:183], v[50:51]
	v_cvt_pk_bf16_f32 v248, v20, v21
	v_cvt_pk_bf16_f32 v249, v22, v23
	v_pk_mul_f32 v[48:49], v[60:61], v[86:87] op_sel_hi:[1,0]
	v_pk_mul_f32 v[50:51], v[62:63], v[86:87] op_sel_hi:[1,0]
	s_waitcnt vmcnt(11)
	v_pk_mul_f32 v[20:21], v[184:185], v[48:49]
	v_pk_mul_f32 v[22:23], v[186:187], v[50:51]
	v_cvt_pk_bf16_f32 v250, v20, v21
	v_cvt_pk_bf16_f32 v251, v22, v23
	s_nop 1
	v_permlane32_swap_b32 v248, v250
	v_permlane32_swap_b32 v249, v251
	global_store_dwordx4 v[252:253], v[248:251], off offset:96
	s_nop 1
	s_waitcnt vmcnt(11)
	v_pk_mul_f32 v[20:21], v[188:189], v[32:33]
	v_pk_mul_f32 v[22:23], v[190:191], v[34:35]
	v_cvt_pk_bf16_f32 v248, v20, v21
	v_cvt_pk_bf16_f32 v249, v22, v23
	v_pk_mul_f32 v[32:33], v[36:37], v[86:87] op_sel_hi:[1,0]
	v_pk_mul_f32 v[34:35], v[38:39], v[86:87] op_sel_hi:[1,0]
	s_waitcnt vmcnt(10)
	v_pk_mul_f32 v[20:21], v[192:193], v[32:33]
	v_pk_mul_f32 v[22:23], v[194:195], v[34:35]
	v_cvt_pk_bf16_f32 v250, v20, v21
	v_cvt_pk_bf16_f32 v251, v22, v23
	s_nop 1
	v_permlane32_swap_b32 v248, v250
	v_permlane32_swap_b32 v249, v251
	global_store_dwordx4 v[252:253], v[248:251], off offset:128
	s_nop 1
	v_pk_mul_f32 v[32:33], v[40:41], v[86:87] op_sel_hi:[1,0]
	v_pk_mul_f32 v[34:35], v[42:43], v[86:87] op_sel_hi:[1,0]
	s_waitcnt vmcnt(10)
	v_pk_mul_f32 v[20:21], v[196:197], v[32:33]
	v_pk_mul_f32 v[22:23], v[198:199], v[34:35]
	v_cvt_pk_bf16_f32 v248, v20, v21
	v_cvt_pk_bf16_f32 v249, v22, v23
	v_pk_mul_f32 v[32:33], v[44:45], v[86:87] op_sel_hi:[1,0]
	v_pk_mul_f32 v[34:35], v[46:47], v[86:87] op_sel_hi:[1,0]
	s_waitcnt vmcnt(9)
	v_pk_mul_f32 v[20:21], v[200:201], v[32:33]
	v_pk_mul_f32 v[22:23], v[202:203], v[34:35]
	v_cvt_pk_bf16_f32 v250, v20, v21
	v_cvt_pk_bf16_f32 v251, v22, v23
	s_nop 1
	v_permlane32_swap_b32 v248, v250
	v_permlane32_swap_b32 v249, v251
	global_store_dwordx4 v[252:253], v[248:251], off offset:160
	s_nop 1
	v_pk_mul_f32 v[32:33], v[150:151], v[86:87] op_sel_hi:[1,0]
	s_waitcnt vmcnt(9)
	v_pk_mul_f32 v[18:19], v[206:207], v[18:19]
	v_pk_mul_f32 v[20:21], v[204:205], v[32:33]
	v_pk_mul_f32 v[22:23], v[84:85], v[86:87] op_sel_hi:[1,0]
	v_cvt_pk_bf16_f32 v248, v20, v21
	v_cvt_pk_bf16_f32 v249, v18, v19
	s_waitcnt vmcnt(8)
	v_pk_mul_f32 v[18:19], v[234:235], v[22:23]
	v_pk_mul_f32 v[16:17], v[236:237], v[16:17]
	v_cvt_pk_bf16_f32 v250, v18, v19
	v_cvt_pk_bf16_f32 v251, v16, v17
	s_nop 1
	v_permlane32_swap_b32 v248, v250
	v_permlane32_swap_b32 v249, v251
	global_store_dwordx4 v[252:253], v[248:251], off offset:192
	s_nop 1
	v_pk_mul_f32 v[20:21], v[30:31], v[86:87] op_sel_hi:[1,0]
	v_pk_mul_f32 v[22:23], v[28:29], v[86:87] op_sel_hi:[1,0]
	s_waitcnt vmcnt(8)
	v_pk_mul_f32 v[16:17], v[238:239], v[20:21]
	v_pk_mul_f32 v[18:19], v[240:241], v[22:23]
	v_cvt_pk_bf16_f32 v248, v16, v17
	v_cvt_pk_bf16_f32 v249, v18, v19
	v_pk_mul_f32 v[20:21], v[24:25], v[86:87] op_sel_hi:[1,0]
	v_pk_mul_f32 v[22:23], v[26:27], v[86:87] op_sel_hi:[1,0]
	s_waitcnt vmcnt(7)
	v_pk_mul_f32 v[16:17], v[242:243], v[20:21]
	v_pk_mul_f32 v[18:19], v[244:245], v[22:23]
	v_cvt_pk_bf16_f32 v250, v16, v17
	v_cvt_pk_bf16_f32 v251, v18, v19
	s_nop 1
	v_permlane32_swap_b32 v248, v250
	v_permlane32_swap_b32 v249, v251
	global_store_dwordx4 v[252:253], v[248:251], off offset:224
	s_nop 1
	s_cbranch_scc1 .LBB0_677
